# v16 + prompt-MLA loop: waves 4-7 run softmax+PV of tile T after the barrier (before QK of tile T+1), waves 0-3 unchanged: complementary MFMA/VALU phases on each SIMD; pure control-flow rotation, bit-i
# baseline (speedup 1.0000x reference)
; template <int MODE> __device__ __forceinline__ void tile_ctx(const AU& U, int tid, TL& C) {
;     constexpr int CPR = MODE == 0 ? 20 : 16, NCH = 64 * CPR, NLD = (NCH + 511) / 512, KC = MODE == 0 ? 12 : 8, KSTR = MODE == 0 ? 208 : 144;
; #pragma unroll
;     for (int i = 0; i < NLD; ++i) { const int c0 = tid + 512 * i; const int c = c0 < NCH ? c0 : c0 - 512;
;         const int row = c / CPR, cc = c % CPR; C.c[i] = c;
;         const bool isk = cc < 8, isr = (MODE == 0) && cc >= 8 && cc < 12; const int vo = cc - (MODE == 0 ? 12 : 8);
;         const unsigned long long kAa = (unsigned long long)U.kA, vAa = (unsigned long long)U.vA, rAa = (unsigned long long)U.rA, kBa = (unsigned long long)U.kB, vBa = (unsigned long long)U.vB, rBa = (unsigned long long)U.rB;
;         const unsigned long long offA = isr ? (unsigned long long)(row * 32 + (cc - 8) * 8) * 2ull : ((unsigned long long)row * (unsigned long long)U.pA + (unsigned long long)((isk ? cc : vo) * 8)) * 2ull;
;         const unsigned long long offB = isr ? (unsigned long long)(row * 32 + (cc - 8) * 8) * 2ull : ((unsigned long long)row * (unsigned long long)U.pB + (unsigned long long)((isk ? cc : vo) * 8)) * 2ull;
;         C.a[i] = (isk ? kAa : (isr ? rAa : vAa)) + offA; C.b[i] = (isk ? kBa : (isr ? rBa : vBa)) + offB;
;         C.sa[i] = (isr ? 64 * 32 : 64 * U.pA) * 2; C.sb[i] = (isr ? 64 * 32 : 64 * U.pB) * 2;
;         C.ld[i] = cc < KC ? row * KSTR + cc * 16 : KB_MAX + row * VSTR + (cc - KC) * 16; }
; }
; template <int MODE> __device__ __forceinline__ void tile_loads(const AU& U, const TL& C, int T, v4u (&pre)[3]) {
;     constexpr int CPR = MODE == 0 ? 20 : 16, NCH = 64 * CPR, NLD = (NCH + 511) / 512;
;     const bool useA = T < U.ntA;
;     if (MODE != 0 && useA && U.kAf) {
; #pragma unroll
;         for (int i = 0; i < NLD; ++i) { const int row = C.c[i] / CPR, cc = C.c[i] % CPR;
;             const float* fs = cc < 8 ? U.kAf + (size_t)(T * 64 + row) * U.pA + cc * 8 : U.vAf + (size_t)(T * 64 + row) * U.pA + (cc - 8) * 8;
;             const f32x4 a = *(const f32x4*)fs, b = *(const f32x4*)(fs + 4); v4u o; o.x = pk2(a[0], a[1]); o.y = pk2(a[2], a[3]); o.z = pk2(b[0], b[1]); o.w = pk2(b[2], b[3]); pre[i] = o; }
;     } else {
;         const int tt = useA ? T : T - U.ntA;
; #pragma unroll
.LBB0_640:
	s_lshl_b32 s1, s0, 11
	s_mov_b64 s[4:5], s[92:93]
	v_add_u32_e32 v2, 0xfffffe00, v27
	v_cmp_gt_i32_e32 vcc, s62, v27
	s_add_u32 s1, s4, s1
	s_addc_u32 s4, s5, 0
	v_cndmask_b32_e32 v2, v2, v27, vcc
	s_lshl_b32 s5, s2, 8
	s_waitcnt vmcnt(0)
	v_mul_hi_i32 v4, v2, s63
	s_add_u32 s15, s1, s5
	v_lshrrev_b32_e32 v5, 31, v4
	v_ashrrev_i32_e32 v4, 3, v4
	s_addc_u32 s16, s4, 0
	v_add_u32_e32 v8, v4, v5
	s_add_u32 s12, s15, 0x80
	v_mul_lo_u32 v4, v8, 20
	s_addc_u32 s13, s16, 0
	s_lshl_b32 s0, s0, 6
	v_readlane_b32 s4, v250, 13
	v_sub_u32_e32 v10, v2, v4
	v_readlane_b32 s5, v250, 14
	s_add_u32 s10, s4, s0
	v_and_b32_e32 v2, -4, v10
	s_addc_u32 s11, s5, 0
	v_cmp_gt_i32_e32 vcc, 8, v10
	v_cmp_ne_u32_e64 s[0:1], 8, v2
	v_add_u32_e32 v2, -12, v10
	s_and_saveexec_b64 s[4:5], s[0:1]
	s_xor_b64 s[0:1], exec, s[4:5]
	v_cndmask_b32_e32 v6, v2, v10, vcc
	v_ashrrev_i32_e32 v9, 31, v8
	v_lshlrev_b32_e32 v6, 3, v6
	v_lshlrev_b64 v[4:5], 10, v[8:9]
	v_ashrrev_i32_e32 v7, 31, v6
	v_lshl_add_u64 v[4:5], v[4:5], 0, v[6:7]
	s_or_saveexec_b64 s[0:1], s[0:1]
	v_mov_b64_e32 v[170:171], 0x20000
	v_mov_b64_e32 v[6:7], s[12:13]
	s_xor_b64 exec, exec, s[0:1]
	v_lshlrev_b32_e32 v4, 5, v8
	v_lshlrev_b32_e32 v5, 3, v10
	v_add3_u32 v4, v5, v4, s64
	v_ashrrev_i32_e32 v5, 31, v4
	v_mov_b64_e32 v[170:171], 0x1000
	v_mov_b64_e32 v[6:7], s[10:11]
	s_or_b64 exec, exec, s[0:1]
	v_cmp_lt_i32_e64 s[0:1], 11, v10
	s_and_saveexec_b64 s[4:5], s[0:1]
	s_xor_b64 s[0:1], exec, s[4:5]
	v_mul_lo_u32 v8, v8, s52
	v_add_u32_e32 v18, 0x3400, v8
	s_andn2_saveexec_b64 s[0:1], s[0:1]
	v_mul_lo_u32 v18, v8, s65
	v_mov_b32_e32 v2, v10
	s_or_b64 exec, exec, s[0:1]
	v_add_u32_e32 v8, 0x200, v27
	v_cmp_gt_i32_e64 s[0:1], s66, v27
	s_nop 1
	v_cndmask_b32_e64 v8, v27, v8, s[0:1]
	v_mul_hi_i32 v9, v8, s63
	v_lshrrev_b32_e32 v10, 31, v9
	v_ashrrev_i32_e32 v9, 3, v9
	v_add_u32_e32 v12, v9, v10
	v_mul_lo_u32 v9, v12, 20
	v_sub_u32_e32 v14, v8, v9
	v_and_b32_e32 v8, -4, v14
	v_cmp_gt_i32_e64 s[4:5], 8, v14
	v_cmp_ne_u32_e64 s[0:1], 8, v8
	v_add_u32_e32 v19, -12, v14
	s_and_saveexec_b64 s[6:7], s[0:1]
	s_xor_b64 s[0:1], exec, s[6:7]
	v_cndmask_b32_e64 v10, v19, v14, s[4:5]
	v_ashrrev_i32_e32 v13, 31, v12
	v_lshlrev_b32_e32 v10, 3, v10
	v_lshlrev_b64 v[8:9], 10, v[12:13]
	v_ashrrev_i32_e32 v11, 31, v10
	v_lshl_add_u64 v[8:9], v[8:9], 0, v[10:11]
	s_or_saveexec_b64 s[0:1], s[0:1]
	v_mov_b64_e32 v[172:173], 0x20000
	v_mov_b64_e32 v[10:11], s[12:13]
	s_xor_b64 exec, exec, s[0:1]
	v_lshlrev_b32_e32 v8, 5, v12
	v_lshlrev_b32_e32 v9, 3, v14
	v_add3_u32 v8, v9, v8, s64
	v_ashrrev_i32_e32 v9, 31, v8
	v_mov_b64_e32 v[172:173], 0x1000
	v_mov_b64_e32 v[10:11], s[10:11]
	s_or_b64 exec, exec, s[0:1]
	v_cmp_lt_i32_e64 s[0:1], 11, v14
	s_and_saveexec_b64 s[6:7], s[0:1]
	s_xor_b64 s[0:1], exec, s[6:7]
	v_mul_lo_u32 v12, v12, s52
	v_add_u32_e32 v20, 0x3400, v12
	s_andn2_saveexec_b64 s[0:1], s[0:1]
	v_mul_lo_u32 v20, v12, s65
	v_mov_b32_e32 v19, v14
	s_or_b64 exec, exec, s[0:1]
	v_cmp_gt_i32_e64 s[0:1], s47, v27
	s_nop 1
	v_cndmask_b32_e64 v12, v203, v236, s[0:1]
	v_add_u32_e32 v13, v12, v27
	v_mul_hi_i32 v12, v13, s63
	v_lshrrev_b32_e32 v14, 31, v12
	v_ashrrev_i32_e32 v12, 3, v12
	v_add_u32_e32 v12, v12, v14
	v_mul_lo_u32 v14, v12, 20
	v_sub_u32_e32 v22, v13, v14
	v_and_b32_e32 v13, -4, v22
	v_cmp_gt_i32_e64 s[0:1], 8, v22
	v_cmp_ne_u32_e64 s[6:7], 8, v13
	v_add_u32_e32 v21, -12, v22
	s_and_saveexec_b64 s[18:19], s[6:7]
	s_xor_b64 s[6:7], exec, s[18:19]
	v_ashrrev_i32_e32 v13, 31, v12
	v_lshlrev_b64 v[14:15], 10, v[12:13]
	v_cndmask_b32_e64 v13, v21, v22, s[0:1]
	v_lshlrev_b32_e32 v16, 3, v13
	v_ashrrev_i32_e32 v17, 31, v16
	v_lshl_add_u64 v[14:15], v[14:15], 0, v[16:17]
	s_or_saveexec_b64 s[6:7], s[6:7]
	v_mov_b64_e32 v[174:175], 0x20000
	v_mov_b64_e32 v[16:17], s[12:13]
	s_xor_b64 exec, exec, s[6:7]
	v_lshlrev_b32_e32 v13, 5, v12
	v_lshlrev_b32_e32 v14, 3, v22
	v_add3_u32 v14, v14, v13, s64
	v_ashrrev_i32_e32 v15, 31, v14
	v_mov_b64_e32 v[174:175], 0x1000
	v_mov_b64_e32 v[16:17], s[10:11]
	s_or_b64 exec, exec, s[6:7]
	v_cmp_lt_i32_e64 s[6:7], 11, v22
	s_and_saveexec_b64 s[10:11], s[6:7]
	s_xor_b64 s[6:7], exec, s[10:11]
	v_mul_lo_u32 v12, v12, s52
	v_add_u32_e32 v13, 0x3400, v12
	s_andn2_saveexec_b64 s[6:7], s[6:7]
	v_mul_lo_u32 v13, v12, s65
	v_mov_b32_e32 v21, v22
	s_or_b64 exec, exec, s[6:7]
	v_mov_b32_e32 v12, s16
	v_mov_b32_e32 v22, s15
	v_cndmask_b32_e64 v17, v17, v12, s[0:1]
	v_cndmask_b32_e64 v16, v16, v22, s[0:1]
	s_sub_i32 s0, 0xfc0, s3
	v_cndmask_b32_e32 v7, v7, v12, vcc
	v_cndmask_b32_e32 v6, v6, v22, vcc
	s_ashr_i32 s3, s0, 6
	v_cndmask_b32_e64 v11, v11, v12, s[4:5]
	v_cndmask_b32_e64 v10, v10, v22, s[4:5]
	v_lshl_add_u64 v[180:181], v[4:5], 1, v[6:7]
	s_min_i32 s4, s3, 1
	v_lshl_add_u64 v[178:179], v[8:9], 1, v[10:11]
	v_mad_i64_i32 v[4:5], s[0:1], v170, s4, v[180:181]
	v_lshl_add_u64 v[176:177], v[14:15], 1, v[16:17]
	global_load_dwordx4 v[34:37], v[180:181], off
	global_load_dwordx4 v[38:41], v[178:179], off
	global_load_dwordx4 v[42:45], v[176:177], off
	global_load_dwordx4 v[122:125], v[4:5], off
	v_mad_i64_i32 v[4:5], s[0:1], v172, s4, v[178:179]
	global_load_dwordx4 v[126:129], v[4:5], off
	v_mad_i64_i32 v[4:5], s[0:1], v174, s4, v[176:177]
	global_load_dwordx4 v[130:133], v[4:5], off
	v_lshl_add_u32 v19, v19, 4, v20
	v_lshl_add_u32 v20, v21, 4, v13
	v_lshlrev_b32_e32 v169, 2, v28
	v_lshrrev_b32_e32 v21, 2, v27
	v_lshl_add_u32 v18, v2, 4, v18
	v_lshlrev_b32_e32 v22, 1, v27
	v_lshlrev_b32_e32 v23, 3, v27
	v_and_or_b32 v46, v21, 3, v169
	v_mov_b32_e32 v16, v3
	v_mov_b32_e32 v17, v3
	v_add_u32_e32 v173, 0x100, v18
	v_and_b32_e32 v47, 32, v22
	v_and_b32_e32 v48, 24, v23
	v_mul_u32_u24_e32 v46, 0xc0, v46
	v_mad_u32_u24 v171, v26, s65, v1
	v_mov_b32_e32 v2, v3
	v_mov_b32_e32 v4, v3
	v_mov_b32_e32 v5, v3
	v_mov_b32_e32 v6, v3
	v_mov_b32_e32 v7, v3
	v_mov_b32_e32 v8, v3
	v_mov_b32_e32 v9, v3
	v_mov_b32_e32 v10, v3
	v_mov_b32_e32 v11, v3
	v_mov_b32_e32 v12, v3
	v_mov_b32_e32 v13, v3
	v_mov_b32_e32 v14, v3
	v_mov_b32_e32 v15, v3
	v_add_u32_e32 v175, 0x100, v19
	v_add_u32_e32 v182, 0x100, v20
	v_mov_b64_e32 v[64:65], v[16:17]
	v_mov_b64_e32 v[32:33], v[16:17]
	v_or3_b32 v183, v46, v47, v48
	s_mov_b32 s11, 1
	s_ashr_i32 s10, s14, 6
	v_mov_b32_e32 v167, 0
	s_mov_b64 s[4:5], -1
	v_mov_b64_e32 v[62:63], v[14:15]
	v_mov_b64_e32 v[60:61], v[12:13]
	v_mov_b64_e32 v[58:59], v[10:11]
	v_mov_b64_e32 v[56:57], v[8:9]
	v_mov_b64_e32 v[54:55], v[6:7]
	v_mov_b64_e32 v[52:53], v[4:5]
	v_mov_b64_e32 v[50:51], v[2:3]
	v_mov_b64_e32 v[30:31], v[14:15]
	v_mov_b64_e32 v[28:29], v[12:13]
	v_mov_b64_e32 v[26:27], v[10:11]
	v_mov_b64_e32 v[24:25], v[8:9]
	v_mov_b64_e32 v[22:23], v[6:7]
	v_mov_b64_e32 v[20:21], v[4:5]
	v_mov_b64_e32 v[18:19], v[2:3]
	s_waitcnt vmcnt(5)
; template <int MODE> __device__ __forceinline__ void attn_unit(const AU& U, LAS unsigned char* lds, const float* rope, const float* biasg) {
;     ...
;     tile_loads<MODE>(U, C, glo, preA); tile_stores<MODE>(lds, C, preA);
;     tile_loads<MODE>(U, C, (glo < ghi ? glo + 1 : ghi), preA);
;     __syncthreads();
	ds_write_b128 v173, v[34:37]
	s_waitcnt vmcnt(4)
	ds_write_b128 v175, v[38:41]
	s_waitcnt vmcnt(3)
	ds_write_b128 v182, v[42:45]
	v_mov_b64_e32 v[48:49], v[16:17]
	v_mov_b64_e32 v[46:47], v[14:15]
	v_mov_b64_e32 v[44:45], v[12:13]
	v_mov_b64_e32 v[42:43], v[10:11]
	v_mov_b64_e32 v[40:41], v[8:9]
	v_mov_b64_e32 v[38:39], v[6:7]
	v_mov_b64_e32 v[36:37], v[4:5]
	v_mov_b64_e32 v[34:35], v[2:3]
	v_readfirstlane_b32 s98, v198
	s_mov_b32 s99, 0
	s_nop 3
	s_lshr_b32 s98, s98, 8
	s_waitcnt lgkmcnt(0)
	s_barrier
	s_branch .LBB0_666

; #define LAS __attribute__((address_space(3)))
; __device__ __forceinline__ float halves_max(float m) { auto rr = __builtin_amdgcn_permlane32_swap(__float_as_uint(m), __float_as_uint(m), false, false); return fmaxf(__uint_as_float(rr[0]), __uint_as_float(rr[1])); }
; #define MFMA32(a, b, c) __builtin_amdgcn_mfma_f32_32x32x16_bf16((a), (b), (c), 0, 0, 0)
; #define MX3_(a, b, c) __builtin_fmaxf(__builtin_fmaxf((a), (b)), (c))
;     constexpr int NS = MODE == 0 ? 6 : 4, KSTR = MODE == 0 ? 208 : 144;
;     const LAS unsigned char* kb = buf + r * KSTR + hi * 16;
; #pragma unroll
;     for (int s = 0; s < NS; ++s) { const bf16x8 a0 = *(const LAS bf16x8*)(kb + 32 * s), a1 = *(const LAS bf16x8*)(kb + 32 * KSTR + 32 * s);
;         if (s == 0) { s0 = MFMA32(a0, qf[0], negm); s1 = MFMA32(a1, qf[0], negm); }
;         else { s0 = MFMA32(a0, qf[s], s0); s1 = MFMA32(a1, qf[s], s1); } }
; }
; template <int MODE> __device__ __forceinline__ void st_sm(int T, int tq, int qpos, int hi, const LAS float* biasl, f32x16& s0, f32x16& s1, f32x16& o0, f32x16& o1, f32x16& negm, float& lrun, bool& fresh) {
;     ...
;     float ma = MX3_(s0[0], s0[1], s1[0]), mb = MX3_(s0[2], s0[3], s1[1]); ma = MX3_(ma, s1[2], s1[3]);
; #pragma unroll
;     for (int i = 4; i < 16; i += 4) { ma = MX3_(ma, s0[i], s0[i + 1]); mb = MX3_(mb, s0[i + 2], s0[i + 3]); ma = MX3_(ma, s1[i], s1[i + 1]); mb = MX3_(mb, s1[i + 2], s1[i + 3]); }
;     ...
;     float mx = halves_max(__builtin_fmaxf(ma, mb));
;     if (fresh || __any(mx > 6.0f)) {
.LBB0_666:
	s_cmp_eq_u32 s99, 1
	s_cbranch_scc0 .Ldf0_top
	s_mov_b32 s99, 2
	s_xor_b64 s[0:1], s[4:5], -1
	s_and_b64 vcc, exec, s[0:1]
	s_branch .Ldf0_sp
.Ldf0_top:
	s_add_i32 s0, s11, 1
	s_min_i32 s6, s0, s3
	s_waitcnt vmcnt(2)
	v_mad_i64_i32 v[4:5], s[0:1], v170, s6, v[180:181]
	s_waitcnt vmcnt(1)
	v_mad_i64_i32 v[8:9], s[0:1], v172, s6, v[178:179]
	s_waitcnt vmcnt(0)
	v_mad_i64_i32 v[12:13], s[0:1], v174, s6, v[176:177]
	global_load_dwordx4 v[4:7], v[4:5], off
	s_add_i32 s13, s11, -1
	global_load_dwordx4 v[8:11], v[8:9], off
	s_cmp_le_i32 s13, s10
	global_load_dwordx4 v[12:15], v[12:13], off
	s_cselect_b64 s[0:1], -1, 0
	s_and_b64 s[0:1], s[8:9], s[0:1]
	s_andn2_b64 vcc, exec, s[0:1]
	s_cbranch_vccnz .LBB0_674
	v_add_u32_e32 v2, v171, v168
	s_xor_b64 s[0:1], s[4:5], -1
	s_and_b64 vcc, exec, s[0:1]
	ds_read_b128 v[66:69], v2
	ds_read_b128 v[134:137], v2 offset:6656
	ds_read_b128 v[138:141], v2 offset:32
	ds_read_b128 v[142:145], v2 offset:6688
	ds_read_b128 v[146:149], v2 offset:64
	ds_read_b128 v[150:153], v2 offset:6720
	ds_read_b128 v[154:157], v2 offset:96
	ds_read_b128 v[158:161], v2 offset:6752
	ds_read_b128 v[162:165], v2 offset:128
	s_waitcnt lgkmcnt(8)
	v_mfma_f32_32x32x16_bf16 v[82:97], v[66:69], v[110:113], v[50:65]
	s_waitcnt lgkmcnt(7)
	v_mfma_f32_32x32x16_bf16 v[66:81], v[134:137], v[110:113], v[50:65]
	ds_read_b128 v[134:137], v2 offset:6784
	s_waitcnt lgkmcnt(7)
	v_mfma_f32_32x32x16_bf16 v[82:97], v[138:141], v[106:109], v[82:97]
	ds_read_b128 v[138:141], v2 offset:160
	s_waitcnt lgkmcnt(7)
	v_mfma_f32_32x32x16_bf16 v[66:81], v[142:145], v[106:109], v[66:81]
	ds_read_b128 v[142:145], v2 offset:6816
	v_add_u32_e32 v2, 0x100, v183
	s_waitcnt lgkmcnt(7)
	v_mfma_f32_32x32x16_bf16 v[82:97], v[146:149], v[102:105], v[82:97]
	s_waitcnt lgkmcnt(6)
	v_mfma_f32_32x32x16_bf16 v[66:81], v[150:153], v[102:105], v[66:81]
	s_waitcnt lgkmcnt(5)
	v_mfma_f32_32x32x16_bf16 v[82:97], v[154:157], v[98:101], v[82:97]
	s_waitcnt lgkmcnt(4)
	v_mfma_f32_32x32x16_bf16 v[66:81], v[158:161], v[98:101], v[66:81]
	s_waitcnt lgkmcnt(3)
	v_mfma_f32_32x32x16_bf16 v[82:97], v[162:165], v[118:121], v[82:97]
	s_waitcnt lgkmcnt(2)
	v_mfma_f32_32x32x16_bf16 v[66:81], v[134:137], v[118:121], v[66:81]
	s_waitcnt lgkmcnt(1)
	v_mfma_f32_32x32x16_bf16 v[82:97], v[138:141], v[114:117], v[82:97]
	s_waitcnt lgkmcnt(0)
	v_mfma_f32_32x32x16_bf16 v[66:81], v[142:145], v[114:117], v[66:81]
	ds_read_b64_tr_b16 v[162:163], v2 offset:13312
	ds_read_b64_tr_b16 v[164:165], v2 offset:14848
	ds_read_b64_tr_b16 v[158:159], v2 offset:13376
	ds_read_b64_tr_b16 v[160:161], v2 offset:14912
	ds_read_b64_tr_b16 v[150:151], v2 offset:16384
	ds_read_b64_tr_b16 v[152:153], v2 offset:17920
	ds_read_b64_tr_b16 v[154:155], v2 offset:16448
	ds_read_b64_tr_b16 v[156:157], v2 offset:17984
	ds_read_b64_tr_b16 v[146:147], v2 offset:19456
	ds_read_b64_tr_b16 v[148:149], v2 offset:20992
	ds_read_b64_tr_b16 v[142:143], v2 offset:19520
	ds_read_b64_tr_b16 v[144:145], v2 offset:21056
	ds_read_b64_tr_b16 v[138:139], v2 offset:22528
	ds_read_b64_tr_b16 v[140:141], v2 offset:24064
	ds_read_b64_tr_b16 v[134:135], v2 offset:22592
	ds_read_b64_tr_b16 v[136:137], v2 offset:24128
	s_cmp_eq_u32 s98, 0
	s_cbranch_scc1 .Ldf0_sp
	s_mov_b32 s99, 1
	s_branch .Ldf0_st
.Ldf0_sp:
	v_max_f32_e32 v2, v83, v83
	v_max_f32_e32 v16, v82, v82
	v_max_f32_e32 v2, v16, v2
	v_max3_f32 v16, v84, v85, v67
	v_max3_f32 v2, v2, v66, v68
	v_max3_f32 v2, v2, v69, v86
	v_max3_f32 v16, v16, v88, v89
	v_max3_f32 v2, v2, v87, v70
	v_max3_f32 v16, v16, v72, v73
	v_max3_f32 v2, v2, v71, v90
	v_max3_f32 v16, v16, v92, v93
	v_max3_f32 v2, v2, v91, v74
	v_max3_f32 v16, v16, v76, v77
	v_max3_f32 v2, v2, v75, v94
	v_max3_f32 v16, v16, v96, v97
	v_max3_f32 v2, v2, v95, v78
	v_max3_f32 v16, v16, v80, v81
	v_max3_f32 v2, v2, v79, v16
	v_mov_b32_e32 v16, v2
	s_nop 1
	v_permlane32_swap_b32_e32 v2, v16
	v_max_f32_e32 v16, v16, v16
	v_max_f32_e32 v2, v2, v2
	v_max_f32_e32 v2, v2, v16
	s_cbranch_vccz .LBB0_669
	v_cmp_lt_f32_e32 vcc, s58, v2
	s_cmp_lg_u64 vcc, 0
	s_cselect_b64 s[0:1], -1, 0
	s_cbranch_execz .LBB0_670
	s_branch .LBB0_671

.LBB0_674:
	s_cmp_lt_u32 s99, 2
	s_cbranch_scc1 .Ldf0_st
	s_cmp_eq_u32 s99, 3
	s_mov_b32 s99, 0
	s_cbranch_scc1 .Ldf_exit_cont
	s_branch .Ldf0_top

; #define LAS __attribute__((address_space(3)))
; #define MFMA32(a, b, c) __builtin_amdgcn_mfma_f32_32x32x16_bf16((a), (b), (c), 0, 0, 0)
;     constexpr int NS = MODE == 0 ? 6 : 4, KSTR = MODE == 0 ? 208 : 144;
;     const LAS unsigned char* kb = buf + r * KSTR + hi * 16;
; #pragma unroll
;     for (int s = 0; s < NS; ++s) { const bf16x8 a0 = *(const LAS bf16x8*)(kb + 32 * s), a1 = *(const LAS bf16x8*)(kb + 32 * KSTR + 32 * s);
;         if (s == 0) { s0 = MFMA32(a0, qf[0], negm); s1 = MFMA32(a1, qf[0], negm); }
;         else { s0 = MFMA32(a0, qf[s], s0); s1 = MFMA32(a1, qf[s], s1); } }
; }
.LBB0_676:
	s_waitcnt lgkmcnt(0)
	s_barrier
	s_andn2_b64 vcc, exec, s[0:1]
	s_mov_b64 s[0:1], -1
	s_cbranch_vccnz .LBB0_680
	s_cmp_eq_u32 s99, 1
	s_cbranch_scc0 .Ldf1_top
	s_mov_b32 s99, 2
	s_xor_b64 s[0:1], s[4:5], -1
	s_and_b64 vcc, exec, s[0:1]
	s_branch .Ldf1_sp
.Ldf1_top:
	s_add_i32 s12, s11, 2
	s_min_i32 s6, s12, s3
	v_mad_i64_i32 v[16:17], s[0:1], v170, s6, v[180:181]
	global_load_dwordx4 v[122:125], v[16:17], off
	v_mad_i64_i32 v[16:17], s[0:1], v172, s6, v[178:179]
	global_load_dwordx4 v[126:129], v[16:17], off
	v_mad_i64_i32 v[16:17], s[0:1], v174, s6, v[176:177]
	global_load_dwordx4 v[130:133], v[16:17], off
	s_cmp_lt_i32 s13, s10
	s_cselect_b64 s[0:1], -1, 0
	s_and_b64 s[0:1], s[8:9], s[0:1]
	s_andn2_b64 vcc, exec, s[0:1]
	s_cbranch_vccnz .LBB0_686
	v_add_u32_e32 v2, v171, v168
	s_xor_b64 s[0:1], s[4:5], -1
	s_and_b64 vcc, exec, s[0:1]
	ds_read_b128 v[66:69], v2 offset:25600
	ds_read_b128 v[134:137], v2 offset:32256
	ds_read_b128 v[138:141], v2 offset:25632
	ds_read_b128 v[142:145], v2 offset:32288
	ds_read_b128 v[146:149], v2 offset:25664
	ds_read_b128 v[150:153], v2 offset:32320
	ds_read_b128 v[154:157], v2 offset:25696
	ds_read_b128 v[158:161], v2 offset:32352
	ds_read_b128 v[162:165], v2 offset:25728
	s_waitcnt lgkmcnt(8)
	v_mfma_f32_32x32x16_bf16 v[82:97], v[66:69], v[110:113], v[50:65]
	s_waitcnt lgkmcnt(7)
	v_mfma_f32_32x32x16_bf16 v[66:81], v[134:137], v[110:113], v[50:65]
	ds_read_b128 v[134:137], v2 offset:32384
	s_waitcnt lgkmcnt(7)
	v_mfma_f32_32x32x16_bf16 v[82:97], v[138:141], v[106:109], v[82:97]
	ds_read_b128 v[138:141], v2 offset:25760
	s_waitcnt lgkmcnt(7)
	v_mfma_f32_32x32x16_bf16 v[66:81], v[142:145], v[106:109], v[66:81]
	ds_read_b128 v[142:145], v2 offset:32416
	v_add_u32_e32 v2, 0x100, v183
	s_waitcnt lgkmcnt(7)
	v_mfma_f32_32x32x16_bf16 v[82:97], v[146:149], v[102:105], v[82:97]
	s_waitcnt lgkmcnt(6)
	v_mfma_f32_32x32x16_bf16 v[66:81], v[150:153], v[102:105], v[66:81]
	s_waitcnt lgkmcnt(5)
	v_mfma_f32_32x32x16_bf16 v[82:97], v[154:157], v[98:101], v[82:97]
	s_waitcnt lgkmcnt(4)
	v_mfma_f32_32x32x16_bf16 v[66:81], v[158:161], v[98:101], v[66:81]
	s_waitcnt lgkmcnt(3)
	v_mfma_f32_32x32x16_bf16 v[82:97], v[162:165], v[118:121], v[82:97]
	s_waitcnt lgkmcnt(2)
	v_mfma_f32_32x32x16_bf16 v[66:81], v[134:137], v[118:121], v[66:81]
	s_waitcnt lgkmcnt(1)
	v_mfma_f32_32x32x16_bf16 v[82:97], v[138:141], v[114:117], v[82:97]
	s_waitcnt lgkmcnt(0)
	v_mfma_f32_32x32x16_bf16 v[66:81], v[142:145], v[114:117], v[66:81]
	ds_read_b64_tr_b16 v[162:163], v2 offset:38912
	ds_read_b64_tr_b16 v[164:165], v2 offset:40448
	ds_read_b64_tr_b16 v[158:159], v2 offset:38976
	ds_read_b64_tr_b16 v[160:161], v2 offset:40512
	ds_read_b64_tr_b16 v[150:151], v2 offset:41984
	ds_read_b64_tr_b16 v[152:153], v2 offset:43520
	ds_read_b64_tr_b16 v[154:155], v2 offset:42048
	ds_read_b64_tr_b16 v[156:157], v2 offset:43584
	ds_read_b64_tr_b16 v[146:147], v2 offset:45056
	ds_read_b64_tr_b16 v[148:149], v2 offset:46592
	ds_read_b64_tr_b16 v[142:143], v2 offset:45120
	ds_read_b64_tr_b16 v[144:145], v2 offset:46656
	ds_read_b64_tr_b16 v[138:139], v2 offset:48128
	ds_read_b64_tr_b16 v[140:141], v2 offset:49664
	ds_read_b64_tr_b16 v[134:135], v2 offset:48192
	ds_read_b64_tr_b16 v[136:137], v2 offset:49728
	s_cmp_eq_u32 s98, 0
	s_cbranch_scc1 .Ldf1_sp
	s_mov_b32 s99, 1
	s_branch .Ldf1_st

.LBB0_686:
	s_cmp_lt_u32 s99, 2
	s_cbranch_scc1 .Ldf1_st
	s_mov_b32 s99, 0
	s_branch .Ldf1_top

; template <int MODE> __device__ __forceinline__ void attn_unit(const AU& U, LAS unsigned char* lds, const float* rope, const float* biasg) {
;     ...
;     for (int T = glo;;) { ATT_ITER(preA, preB); ATT_ITER(preB, preA); }
;     ...
;     if (active) {
.LBB0_688:
	s_cmp_eq_u32 s99, 1
	s_cbranch_scc0 .Ldf_exit_cont
	s_mov_b32 s99, 3
	s_xor_b64 s[0:1], s[4:5], -1
	s_and_b64 vcc, exec, s[0:1]
	s_branch .Ldf0_sp
